# layer-0 context-query neighbourhood-attention units also use the hand-written tile code (4 ctx tiles, counted waits)
# speedup vs baseline: 1.1022x; 1.0046x over previous
.LBB0_490:
	s_cmpk_gt_i32 s16, 0xff
	s_mov_b64 s[0:1], -1
	s_cbranch_scc0 .LBB0_502
	s_add_i32 s0, s16, 0xffffff00
	s_lshr_b32 s5, s0, 2
	s_and_b32 s1, s16, 3
	s_lshl_b32 s17, s5, 8
	s_add_i32 s17, s17, 0x4000
	s_lshl_b32 s8, s1, 6
	s_add_i32 s8, s8, s17
	s_mov_b32 s9, s17
	v_readlane_b32 s18, v255, 12
	v_readlane_b32 s19, v255, 13
	v_mbcnt_lo_u32_b32 v237, -1, 0
	v_mbcnt_hi_u32_b32 v237, -1, v237
	v_and_b32_e32 v238, 31, v237
	v_lshrrev_b32_e32 v239, 5, v237
	v_add_u32_e32 v180, s8, v238
	v_mov_b32_e32 v181, 0
	v_mov_b32_e32 v177, 0
	v_add_u32_e32 v176, 32, v180
	v_lshlrev_b32_e32 v174, 2, v239
	v_lshlrev_b32_e32 v246, 4, v239
	v_mov_b32_e32 v247, 0
	v_lshl_add_u64 v[246:247], v[246:247], 0, s[18:19]
	v_mad_i64_i32 v[248:249], s[0:1], v180, s71, v[246:247]
	v_mad_i64_i32 v[246:247], s[0:1], v176, s71, v[246:247]
	global_load_dwordx4 v[128:131], v[248:249], off
	global_load_dwordx4 v[132:135], v[248:249], off offset:32
	global_load_dwordx4 v[136:139], v[248:249], off offset:64
	global_load_dwordx4 v[140:143], v[248:249], off offset:96
	global_load_dwordx4 v[144:147], v[246:247], off
	global_load_dwordx4 v[148:151], v[246:247], off offset:32
	global_load_dwordx4 v[152:155], v[246:247], off offset:64
	global_load_dwordx4 v[156:159], v[246:247], off offset:96
	s_mul_i32 s12, s9, 0x1200
	s_add_u32 s20, s18, s12
	s_addc_u32 s21, s19, 0
	s_add_u32 s22, s20, 0x800
	s_addc_u32 s23, s21, 0
	s_add_u32 s20, s20, 0x400
	s_addc_u32 s21, s21, 0
	v_lshrrev_b32_e32 v214, 3, v237
	v_mul_u32_u24_e32 v214, 0x1200, v214
	v_lshrrev_b32_e32 v215, 4, v237
	v_xor_b32_e32 v215, v215, v237
	v_and_b32_e32 v215, 7, v215
	v_lshl_add_u32 v234, v215, 4, v214
	v_xor_b32_e32 v235, 64, v234
	v_lshrrev_b32_e32 v214, 2, v238
	v_mul_u32_u24_e32 v214, 0x1200, v214
	v_lshl_add_u32 v214, v239, 6, v214
	v_and_b32_e32 v215, 3, v237
	v_lshl_add_u32 v236, v215, 4, v214
	s_add_i32 m0, s87, 0x2000
	s_nop 0
	global_load_lds_dwordx4 v234, s[20:21]
	s_add_i32 m0, s87, 0x2400
	s_add_u32 s28, s20, 0x9000
	s_addc_u32 s29, s21, 0
	global_load_lds_dwordx4 v235, s[28:29]
	s_add_i32 m0, s87, 0x2800
	s_add_u32 s28, s20, 0x12000
	s_addc_u32 s29, s21, 0
	global_load_lds_dwordx4 v234, s[28:29]
	s_add_i32 m0, s87, 0x2c00
	s_add_u32 s28, s20, 0x1b000
	s_addc_u32 s29, s21, 0
	global_load_lds_dwordx4 v235, s[28:29]
	s_add_i32 m0, s87, 0x3000
	s_add_u32 s28, s20, 0x24000
	s_addc_u32 s29, s21, 0
	global_load_lds_dwordx4 v234, s[28:29]
	s_add_i32 m0, s87, 0x3400
	s_add_u32 s28, s20, 0x2d000
	s_addc_u32 s29, s21, 0
	global_load_lds_dwordx4 v235, s[28:29]
	s_add_i32 m0, s87, 0x3800
	s_add_u32 s28, s20, 0x36000
	s_addc_u32 s29, s21, 0
	global_load_lds_dwordx4 v234, s[28:29]
	s_add_i32 m0, s87, 0x3c00
	s_add_u32 s28, s20, 0x3f000
	s_addc_u32 s29, s21, 0
	global_load_lds_dwordx4 v235, s[28:29]
	s_mov_b32 m0, s87
	s_nop 0
	global_load_lds_dwordx4 v236, s[22:23]
	s_add_i32 m0, s87, 0x400
	s_add_u32 s28, s22, 0x9000
	s_addc_u32 s29, s23, 0
	global_load_lds_dwordx4 v236, s[28:29]
	s_add_i32 m0, s87, 0x800
	s_add_u32 s28, s22, 0x12000
	s_addc_u32 s29, s23, 0
	global_load_lds_dwordx4 v236, s[28:29]
	s_add_i32 m0, s87, 0xc00
	s_add_u32 s28, s22, 0x1b000
	s_addc_u32 s29, s23, 0
	global_load_lds_dwordx4 v236, s[28:29]
	s_add_i32 m0, s87, 0x1000
	s_add_u32 s28, s22, 0x24000
	s_addc_u32 s29, s23, 0
	global_load_lds_dwordx4 v236, s[28:29]
	s_add_i32 m0, s87, 0x1400
	s_add_u32 s28, s22, 0x2d000
	s_addc_u32 s29, s23, 0
	global_load_lds_dwordx4 v236, s[28:29]
	s_add_i32 m0, s87, 0x1800
	s_add_u32 s28, s22, 0x36000
	s_addc_u32 s29, s23, 0
	global_load_lds_dwordx4 v236, s[28:29]
	s_add_i32 m0, s87, 0x1c00
	s_add_u32 s28, s22, 0x3f000
	s_addc_u32 s29, s23, 0
	global_load_lds_dwordx4 v236, s[28:29]
	v_lshlrev_b32_e32 v214, 7, v238
	v_add_u32_e32 v214, s87, v214
	v_lshrrev_b32_e32 v215, 1, v237
	v_mov_b32_e32 v219, v239
	v_xor_b32_e32 v219, v219, v215
	v_and_b32_e32 v219, 7, v219
	v_lshl_add_u32 v228, v219, 4, v214
	v_add_u32_e32 v219, 2, v239
	v_xor_b32_e32 v219, v219, v215
	v_and_b32_e32 v219, 7, v219
	v_lshl_add_u32 v229, v219, 4, v214
	v_add_u32_e32 v219, 4, v239
	v_xor_b32_e32 v219, v219, v215
	v_and_b32_e32 v219, 7, v219
	v_lshl_add_u32 v230, v219, 4, v214
	v_add_u32_e32 v219, 6, v239
	v_xor_b32_e32 v219, v219, v215
	v_and_b32_e32 v219, 7, v219
	v_lshl_add_u32 v231, v219, 4, v214
	v_lshrrev_b32_e32 v214, 2, v237
	v_and_b32_e32 v214, 3, v214
	v_lshl_or_b32 v214, v239, 2, v214
	v_lshlrev_b32_e32 v214, 6, v214
	v_lshlrev_b32_e32 v215, 1, v237
	v_and_b32_e32 v215, 32, v215
	v_and_b32_e32 v219, 3, v237
	v_lshlrev_b32_e32 v219, 3, v219
	v_add3_u32 v232, v214, v215, v219
	v_add_u32_e32 v232, s87, v232
	v_mov_b32_e32 v0, 0
	v_mov_b32_e32 v1, 0
	v_mov_b32_e32 v2, 0
	v_mov_b32_e32 v3, 0
	v_mov_b32_e32 v4, 0
	v_mov_b32_e32 v5, 0
	v_mov_b32_e32 v6, 0
	v_mov_b32_e32 v7, 0
	v_mov_b32_e32 v8, 0
	v_mov_b32_e32 v9, 0
	v_mov_b32_e32 v10, 0
	v_mov_b32_e32 v11, 0
	v_mov_b32_e32 v12, 0
	v_mov_b32_e32 v13, 0
	v_mov_b32_e32 v14, 0
	v_mov_b32_e32 v15, 0
	v_mov_b32_e32 v16, 0
	v_mov_b32_e32 v17, 0
	v_mov_b32_e32 v18, 0
	v_mov_b32_e32 v19, 0
	v_mov_b32_e32 v20, 0
	v_mov_b32_e32 v21, 0
	v_mov_b32_e32 v22, 0
	v_mov_b32_e32 v23, 0
	v_mov_b32_e32 v24, 0
	v_mov_b32_e32 v25, 0
	v_mov_b32_e32 v26, 0
	v_mov_b32_e32 v27, 0
	v_mov_b32_e32 v28, 0
	v_mov_b32_e32 v29, 0
	v_mov_b32_e32 v30, 0
	v_mov_b32_e32 v31, 0
	v_mov_b32_e32 v32, 0
	v_mov_b32_e32 v33, 0
	v_mov_b32_e32 v34, 0
	v_mov_b32_e32 v35, 0
	v_mov_b32_e32 v36, 0
	v_mov_b32_e32 v37, 0
	v_mov_b32_e32 v38, 0
	v_mov_b32_e32 v39, 0
	v_mov_b32_e32 v40, 0
	v_mov_b32_e32 v41, 0
	v_mov_b32_e32 v42, 0
	v_mov_b32_e32 v43, 0
	v_mov_b32_e32 v44, 0
	v_mov_b32_e32 v45, 0
	v_mov_b32_e32 v46, 0
	v_mov_b32_e32 v47, 0
	v_mov_b32_e32 v48, 0
	v_mov_b32_e32 v49, 0
	v_mov_b32_e32 v50, 0
	v_mov_b32_e32 v51, 0
	v_mov_b32_e32 v52, 0
	v_mov_b32_e32 v53, 0
	v_mov_b32_e32 v54, 0
	v_mov_b32_e32 v55, 0
	v_mov_b32_e32 v56, 0
	v_mov_b32_e32 v57, 0
	v_mov_b32_e32 v58, 0
	v_mov_b32_e32 v59, 0
	v_mov_b32_e32 v60, 0
	v_mov_b32_e32 v61, 0
	v_mov_b32_e32 v62, 0
	v_mov_b32_e32 v63, 0
	v_mov_b32_e32 v178, 0
	v_mov_b32_e32 v179, 0
	v_mov_b32_e32 v206, 0
	v_mov_b32_e32 v207, 0
	s_mov_b32 s24, 0
.Lnc_ctx:
	s_add_u32 s20, s20, 0x48000
	s_addc_u32 s21, s21, 0
	s_add_u32 s22, s22, 0x48000
	s_addc_u32 s23, s23, 0
	s_waitcnt vmcnt(8)
	ds_read_b128 v[162:165], v228 offset:8192
	ds_read_b128 v[166:169], v229 offset:8192
	ds_read_b128 v[170:173], v230 offset:8192
	ds_read_b128 v[182:185], v231 offset:8192
	s_waitcnt lgkmcnt(3)
	v_mfma_f32_32x32x16_bf16 v[64:79], v[162:165], v[128:131], 0
	ds_read_b128 v[186:189], v228 offset:12288
	ds_read_b128 v[190:193], v229 offset:12288
	ds_read_b128 v[194:197], v230 offset:12288
	ds_read_b128 v[198:201], v231 offset:12288
	s_waitcnt lgkmcnt(6)
	v_mfma_f32_32x32x16_bf16 v[64:79], v[166:169], v[132:135], v[64:79]
	s_waitcnt lgkmcnt(5)
	v_mfma_f32_32x32x16_bf16 v[64:79], v[170:173], v[136:139], v[64:79]
	s_waitcnt lgkmcnt(4)
	v_mfma_f32_32x32x16_bf16 v[64:79], v[182:185], v[140:143], v[64:79]
	v_mfma_f32_32x32x16_bf16 v[96:111], v[162:165], v[144:147], 0
	s_nop 7
	s_nop 2
	v_exp_f32_e32 v64, v64
	v_exp_f32_e32 v65, v65
	v_exp_f32_e32 v66, v66
	v_exp_f32_e32 v67, v67
	v_exp_f32_e32 v68, v68
	v_mfma_f32_32x32x16_bf16 v[96:111], v[166:169], v[148:151], v[96:111]
	v_exp_f32_e32 v69, v69
	v_exp_f32_e32 v70, v70
	v_exp_f32_e32 v71, v71
	v_exp_f32_e32 v72, v72
	v_exp_f32_e32 v73, v73
	v_mfma_f32_32x32x16_bf16 v[96:111], v[170:173], v[152:155], v[96:111]
	v_exp_f32_e32 v74, v74
	v_exp_f32_e32 v75, v75
	v_exp_f32_e32 v76, v76
	v_exp_f32_e32 v77, v77
	v_exp_f32_e32 v78, v78
	v_mfma_f32_32x32x16_bf16 v[96:111], v[182:185], v[156:159], v[96:111]
	v_exp_f32_e32 v79, v79
	v_add_f32_e32 v178, v64, v178
	v_add_f32_e32 v206, v65, v206
	v_add_f32_e32 v178, v66, v178
	v_add_f32_e32 v206, v67, v206
	s_waitcnt lgkmcnt(3)
	v_mfma_f32_32x32x16_bf16 v[80:95], v[186:189], v[128:131], 0
	v_add_f32_e32 v178, v68, v178
	v_add_f32_e32 v206, v69, v206
	v_add_f32_e32 v178, v70, v178
	v_add_f32_e32 v206, v71, v206
	v_add_f32_e32 v178, v72, v178
	s_waitcnt lgkmcnt(2)
	v_mfma_f32_32x32x16_bf16 v[80:95], v[190:193], v[132:135], v[80:95]
	v_add_f32_e32 v206, v73, v206
	v_add_f32_e32 v178, v74, v178
	v_add_f32_e32 v206, v75, v206
	v_add_f32_e32 v178, v76, v178
	v_add_f32_e32 v206, v77, v206
	s_waitcnt lgkmcnt(1)
	v_mfma_f32_32x32x16_bf16 v[80:95], v[194:197], v[136:139], v[80:95]
	v_add_f32_e32 v178, v78, v178
	v_add_f32_e32 v206, v79, v206
	v_cvt_pk_bf16_f32 v64, v64, v65
	v_cvt_pk_bf16_f32 v65, v66, v67
	v_cvt_pk_bf16_f32 v66, v68, v69
	s_waitcnt lgkmcnt(0)
	v_mfma_f32_32x32x16_bf16 v[80:95], v[198:201], v[140:143], v[80:95]
	v_cvt_pk_bf16_f32 v67, v70, v71
	v_cvt_pk_bf16_f32 v68, v72, v73
	v_cvt_pk_bf16_f32 v69, v74, v75
	v_cvt_pk_bf16_f32 v70, v76, v77
	v_cvt_pk_bf16_f32 v71, v78, v79
	v_mfma_f32_32x32x16_bf16 v[112:127], v[186:189], v[144:147], 0
	s_add_i32 m0, s87, 0x2000
	s_add_u32 s28, s20, 0x0
	s_addc_u32 s29, s21, 0
	global_load_lds_dwordx4 v234, s[28:29]
	s_add_i32 m0, s87, 0x2400
	s_add_u32 s28, s20, 0x9000
	s_addc_u32 s29, s21, 0
	global_load_lds_dwordx4 v235, s[28:29]
	v_exp_f32_e32 v96, v96
	v_exp_f32_e32 v97, v97
	v_exp_f32_e32 v98, v98
	v_exp_f32_e32 v99, v99
	v_exp_f32_e32 v100, v100
	v_mfma_f32_32x32x16_bf16 v[112:127], v[190:193], v[148:151], v[112:127]
	s_add_i32 m0, s87, 0x2800
	s_add_u32 s28, s20, 0x12000
	s_addc_u32 s29, s21, 0
	global_load_lds_dwordx4 v234, s[28:29]
	s_add_i32 m0, s87, 0x2c00
	s_add_u32 s28, s20, 0x1b000
	s_addc_u32 s29, s21, 0
	global_load_lds_dwordx4 v235, s[28:29]
	v_exp_f32_e32 v101, v101
	v_exp_f32_e32 v102, v102
	v_exp_f32_e32 v103, v103
	v_exp_f32_e32 v104, v104
	v_exp_f32_e32 v105, v105
	v_mfma_f32_32x32x16_bf16 v[112:127], v[194:197], v[152:155], v[112:127]
	s_add_i32 m0, s87, 0x3000
	s_add_u32 s28, s20, 0x24000
	s_addc_u32 s29, s21, 0
	global_load_lds_dwordx4 v234, s[28:29]
	s_add_i32 m0, s87, 0x3400
	s_add_u32 s28, s20, 0x2d000
	s_addc_u32 s29, s21, 0
	global_load_lds_dwordx4 v235, s[28:29]
	v_exp_f32_e32 v106, v106
	v_exp_f32_e32 v107, v107
	v_exp_f32_e32 v108, v108
	v_exp_f32_e32 v109, v109
	v_exp_f32_e32 v110, v110
	v_mfma_f32_32x32x16_bf16 v[112:127], v[198:201], v[156:159], v[112:127]
	s_add_i32 m0, s87, 0x3800
	s_add_u32 s28, s20, 0x36000
	s_addc_u32 s29, s21, 0
	global_load_lds_dwordx4 v234, s[28:29]
	s_add_i32 m0, s87, 0x3c00
	s_add_u32 s28, s20, 0x3f000
	s_addc_u32 s29, s21, 0
	global_load_lds_dwordx4 v235, s[28:29]
	v_exp_f32_e32 v111, v111
	v_add_f32_e32 v179, v96, v179
	v_add_f32_e32 v207, v97, v207
	v_add_f32_e32 v179, v98, v179
	v_add_f32_e32 v207, v99, v207
	s_waitcnt vmcnt(8)
	ds_read_b64_tr_b16 v[202:203], v232
	ds_read_b64_tr_b16 v[204:205], v232 offset:1024
	ds_read_b64_tr_b16 v[210:211], v232 offset:512
	ds_read_b64_tr_b16 v[212:213], v232 offset:1536
	ds_read_b64_tr_b16 v[220:221], v232 offset:2048
	ds_read_b64_tr_b16 v[222:223], v232 offset:3072
	v_add_f32_e32 v179, v100, v179
	v_add_f32_e32 v207, v101, v207
	v_add_f32_e32 v179, v102, v179
	v_add_f32_e32 v207, v103, v207
	v_add_f32_e32 v179, v104, v179
	v_add_f32_e32 v207, v105, v207
	s_waitcnt lgkmcnt(4)
	v_mfma_f32_32x32x16_bf16 v[48:63], v[202:205], v[64:67], v[48:63]
	v_add_f32_e32 v179, v106, v179
	v_add_f32_e32 v207, v107, v207
	v_add_f32_e32 v179, v108, v179
	v_add_f32_e32 v207, v109, v207
	v_add_f32_e32 v179, v110, v179
	v_add_f32_e32 v207, v111, v207
	v_cvt_pk_bf16_f32 v96, v96, v97
	v_cvt_pk_bf16_f32 v97, v98, v99
	v_cvt_pk_bf16_f32 v98, v100, v101
	v_cvt_pk_bf16_f32 v99, v102, v103
	v_cvt_pk_bf16_f32 v100, v104, v105
	v_cvt_pk_bf16_f32 v101, v106, v107
	v_cvt_pk_bf16_f32 v102, v108, v109
	v_cvt_pk_bf16_f32 v103, v110, v111
	v_mfma_f32_32x32x16_bf16 v[16:31], v[202:205], v[96:99], v[16:31]
	ds_read_b64_tr_b16 v[224:225], v232 offset:2560
	ds_read_b64_tr_b16 v[226:227], v232 offset:3584
	v_exp_f32_e32 v80, v80
	v_exp_f32_e32 v81, v81
	v_exp_f32_e32 v82, v82
	v_exp_f32_e32 v83, v83
	v_exp_f32_e32 v84, v84
	v_exp_f32_e32 v85, v85
	v_exp_f32_e32 v86, v86
	v_exp_f32_e32 v87, v87
	s_waitcnt lgkmcnt(4)
	v_mfma_f32_32x32x16_bf16 v[32:47], v[210:213], v[64:67], v[32:47]
	v_exp_f32_e32 v88, v88
	v_exp_f32_e32 v89, v89
	v_exp_f32_e32 v90, v90
	v_exp_f32_e32 v91, v91
	v_exp_f32_e32 v92, v92
	v_exp_f32_e32 v93, v93
	v_exp_f32_e32 v94, v94
	v_exp_f32_e32 v95, v95
	v_mfma_f32_32x32x16_bf16 v[0:15], v[210:213], v[96:99], v[0:15]
	ds_read_b64_tr_b16 v[202:203], v232 offset:4096
	ds_read_b64_tr_b16 v[204:205], v232 offset:5120
	v_add_f32_e32 v178, v80, v178
	v_add_f32_e32 v206, v81, v206
	v_add_f32_e32 v178, v82, v178
	v_add_f32_e32 v206, v83, v206
	v_add_f32_e32 v178, v84, v178
	v_add_f32_e32 v206, v85, v206
	v_add_f32_e32 v178, v86, v178
	v_add_f32_e32 v206, v87, v206
	s_waitcnt lgkmcnt(4)
	v_mfma_f32_32x32x16_bf16 v[48:63], v[220:223], v[68:71], v[48:63]
	v_add_f32_e32 v178, v88, v178
	v_add_f32_e32 v206, v89, v206
	v_add_f32_e32 v178, v90, v178
	v_add_f32_e32 v206, v91, v206
	v_add_f32_e32 v178, v92, v178
	v_add_f32_e32 v206, v93, v206
	v_add_f32_e32 v178, v94, v178
	v_add_f32_e32 v206, v95, v206
	v_mfma_f32_32x32x16_bf16 v[16:31], v[220:223], v[100:103], v[16:31]
	ds_read_b64_tr_b16 v[210:211], v232 offset:4608
	ds_read_b64_tr_b16 v[212:213], v232 offset:5632
	v_cvt_pk_bf16_f32 v80, v80, v81
	v_cvt_pk_bf16_f32 v81, v82, v83
	v_cvt_pk_bf16_f32 v82, v84, v85
	v_cvt_pk_bf16_f32 v83, v86, v87
	v_cvt_pk_bf16_f32 v84, v88, v89
	v_cvt_pk_bf16_f32 v85, v90, v91
	v_cvt_pk_bf16_f32 v86, v92, v93
	v_cvt_pk_bf16_f32 v87, v94, v95
	s_waitcnt lgkmcnt(4)
	v_mfma_f32_32x32x16_bf16 v[32:47], v[224:227], v[68:71], v[32:47]
	v_exp_f32_e32 v112, v112
	v_exp_f32_e32 v113, v113
	v_exp_f32_e32 v114, v114
	v_exp_f32_e32 v115, v115
	v_exp_f32_e32 v116, v116
	v_exp_f32_e32 v117, v117
	v_exp_f32_e32 v118, v118
	v_exp_f32_e32 v119, v119
	v_mfma_f32_32x32x16_bf16 v[0:15], v[224:227], v[100:103], v[0:15]
	ds_read_b64_tr_b16 v[220:221], v232 offset:6144
	ds_read_b64_tr_b16 v[222:223], v232 offset:7168
	v_exp_f32_e32 v120, v120
	v_exp_f32_e32 v121, v121
	v_exp_f32_e32 v122, v122
	v_exp_f32_e32 v123, v123
	v_exp_f32_e32 v124, v124
	v_exp_f32_e32 v125, v125
	v_exp_f32_e32 v126, v126
	v_exp_f32_e32 v127, v127
	s_waitcnt lgkmcnt(4)
	v_mfma_f32_32x32x16_bf16 v[48:63], v[202:205], v[80:83], v[48:63]
	v_add_f32_e32 v179, v112, v179
	v_add_f32_e32 v207, v113, v207
	v_add_f32_e32 v179, v114, v179
	v_add_f32_e32 v207, v115, v207
	v_add_f32_e32 v179, v116, v179
	v_add_f32_e32 v207, v117, v207
	v_add_f32_e32 v179, v118, v179
	v_add_f32_e32 v207, v119, v207
	v_add_f32_e32 v179, v120, v179
	v_add_f32_e32 v207, v121, v207
	v_add_f32_e32 v179, v122, v179
	v_add_f32_e32 v207, v123, v207
	v_add_f32_e32 v179, v124, v179
	v_add_f32_e32 v207, v125, v207
	v_add_f32_e32 v179, v126, v179
	v_add_f32_e32 v207, v127, v207
	v_cvt_pk_bf16_f32 v112, v112, v113
	v_cvt_pk_bf16_f32 v113, v114, v115
	v_cvt_pk_bf16_f32 v114, v116, v117
	v_cvt_pk_bf16_f32 v115, v118, v119
	v_cvt_pk_bf16_f32 v116, v120, v121
	v_cvt_pk_bf16_f32 v117, v122, v123
	v_cvt_pk_bf16_f32 v118, v124, v125
	v_cvt_pk_bf16_f32 v119, v126, v127
	v_mfma_f32_32x32x16_bf16 v[16:31], v[202:205], v[112:115], v[16:31]
	ds_read_b64_tr_b16 v[224:225], v232 offset:6656
	ds_read_b64_tr_b16 v[226:227], v232 offset:7680
	s_waitcnt lgkmcnt(4)
	v_mfma_f32_32x32x16_bf16 v[32:47], v[210:213], v[80:83], v[32:47]
	v_mfma_f32_32x32x16_bf16 v[0:15], v[210:213], v[112:115], v[0:15]
	s_waitcnt lgkmcnt(2)
	v_mfma_f32_32x32x16_bf16 v[48:63], v[220:223], v[84:87], v[48:63]
	v_mfma_f32_32x32x16_bf16 v[16:31], v[220:223], v[116:119], v[16:31]
	s_waitcnt lgkmcnt(0)
	v_mfma_f32_32x32x16_bf16 v[32:47], v[224:227], v[84:87], v[32:47]
	v_mfma_f32_32x32x16_bf16 v[0:15], v[224:227], v[116:119], v[0:15]
	s_waitcnt lgkmcnt(0)
	s_add_i32 m0, s87, 0x0
	s_add_u32 s28, s22, 0x0
	s_addc_u32 s29, s23, 0
	global_load_lds_dwordx4 v236, s[28:29]
	s_add_i32 m0, s87, 0x400
	s_add_u32 s28, s22, 0x9000
	s_addc_u32 s29, s23, 0
	global_load_lds_dwordx4 v236, s[28:29]
	s_add_i32 m0, s87, 0x800
	s_add_u32 s28, s22, 0x12000
	s_addc_u32 s29, s23, 0
	global_load_lds_dwordx4 v236, s[28:29]
	s_add_i32 m0, s87, 0xc00
	s_add_u32 s28, s22, 0x1b000
	s_addc_u32 s29, s23, 0
	global_load_lds_dwordx4 v236, s[28:29]
	s_add_i32 m0, s87, 0x1000
	s_add_u32 s28, s22, 0x24000
	s_addc_u32 s29, s23, 0
	global_load_lds_dwordx4 v236, s[28:29]
	s_add_i32 m0, s87, 0x1400
	s_add_u32 s28, s22, 0x2d000
	s_addc_u32 s29, s23, 0
	global_load_lds_dwordx4 v236, s[28:29]
	s_add_i32 m0, s87, 0x1800
	s_add_u32 s28, s22, 0x36000
	s_addc_u32 s29, s23, 0
	global_load_lds_dwordx4 v236, s[28:29]
	s_add_i32 m0, s87, 0x1c00
	s_add_u32 s28, s22, 0x3f000
	s_addc_u32 s29, s23, 0
	global_load_lds_dwordx4 v236, s[28:29]
	s_add_i32 s24, s24, 1
	s_cmp_lt_u32 s24, 3
	s_cbranch_scc1 .Lnc_ctx
	s_waitcnt vmcnt(8)
	ds_read_b128 v[162:165], v228 offset:8192
	ds_read_b128 v[166:169], v229 offset:8192
	ds_read_b128 v[170:173], v230 offset:8192
	ds_read_b128 v[182:185], v231 offset:8192
	s_waitcnt lgkmcnt(3)
	v_mfma_f32_32x32x16_bf16 v[64:79], v[162:165], v[128:131], 0
	ds_read_b128 v[186:189], v228 offset:12288
	ds_read_b128 v[190:193], v229 offset:12288
	ds_read_b128 v[194:197], v230 offset:12288
	ds_read_b128 v[198:201], v231 offset:12288
	s_waitcnt lgkmcnt(6)
	v_mfma_f32_32x32x16_bf16 v[64:79], v[166:169], v[132:135], v[64:79]
	s_waitcnt lgkmcnt(5)
	v_mfma_f32_32x32x16_bf16 v[64:79], v[170:173], v[136:139], v[64:79]
	s_waitcnt lgkmcnt(4)
	v_mfma_f32_32x32x16_bf16 v[64:79], v[182:185], v[140:143], v[64:79]
	v_mfma_f32_32x32x16_bf16 v[96:111], v[162:165], v[144:147], 0
	s_nop 7
	s_nop 2
	v_exp_f32_e32 v64, v64
	v_exp_f32_e32 v65, v65
	v_exp_f32_e32 v66, v66
	v_exp_f32_e32 v67, v67
	v_exp_f32_e32 v68, v68
	v_mfma_f32_32x32x16_bf16 v[96:111], v[166:169], v[148:151], v[96:111]
	v_exp_f32_e32 v69, v69
	v_exp_f32_e32 v70, v70
	v_exp_f32_e32 v71, v71
	v_exp_f32_e32 v72, v72
	v_exp_f32_e32 v73, v73
	v_mfma_f32_32x32x16_bf16 v[96:111], v[170:173], v[152:155], v[96:111]
	v_exp_f32_e32 v74, v74
	v_exp_f32_e32 v75, v75
	v_exp_f32_e32 v76, v76
	v_exp_f32_e32 v77, v77
	v_exp_f32_e32 v78, v78
	v_mfma_f32_32x32x16_bf16 v[96:111], v[182:185], v[156:159], v[96:111]
	v_exp_f32_e32 v79, v79
	v_add_f32_e32 v178, v64, v178
	v_add_f32_e32 v206, v65, v206
	v_add_f32_e32 v178, v66, v178
	v_add_f32_e32 v206, v67, v206
	s_waitcnt lgkmcnt(3)
	v_mfma_f32_32x32x16_bf16 v[80:95], v[186:189], v[128:131], 0
	v_add_f32_e32 v178, v68, v178
	v_add_f32_e32 v206, v69, v206
	v_add_f32_e32 v178, v70, v178
	v_add_f32_e32 v206, v71, v206
	v_add_f32_e32 v178, v72, v178
	s_waitcnt lgkmcnt(2)
	v_mfma_f32_32x32x16_bf16 v[80:95], v[190:193], v[132:135], v[80:95]
	v_add_f32_e32 v206, v73, v206
	v_add_f32_e32 v178, v74, v178
	v_add_f32_e32 v206, v75, v206
	v_add_f32_e32 v178, v76, v178
	v_add_f32_e32 v206, v77, v206
	s_waitcnt lgkmcnt(1)
	v_mfma_f32_32x32x16_bf16 v[80:95], v[194:197], v[136:139], v[80:95]
	v_add_f32_e32 v178, v78, v178
	v_add_f32_e32 v206, v79, v206
	v_cvt_pk_bf16_f32 v64, v64, v65
	v_cvt_pk_bf16_f32 v65, v66, v67
	v_cvt_pk_bf16_f32 v66, v68, v69
	s_waitcnt lgkmcnt(0)
	v_mfma_f32_32x32x16_bf16 v[80:95], v[198:201], v[140:143], v[80:95]
	v_cvt_pk_bf16_f32 v67, v70, v71
	v_cvt_pk_bf16_f32 v68, v72, v73
	v_cvt_pk_bf16_f32 v69, v74, v75
	v_cvt_pk_bf16_f32 v70, v76, v77
	v_cvt_pk_bf16_f32 v71, v78, v79
	v_mfma_f32_32x32x16_bf16 v[112:127], v[186:189], v[144:147], 0
	v_exp_f32_e32 v96, v96
	v_exp_f32_e32 v97, v97
	v_exp_f32_e32 v98, v98
	v_exp_f32_e32 v99, v99
	v_exp_f32_e32 v100, v100
	v_mfma_f32_32x32x16_bf16 v[112:127], v[190:193], v[148:151], v[112:127]
	v_exp_f32_e32 v101, v101
	v_exp_f32_e32 v102, v102
	v_exp_f32_e32 v103, v103
	v_exp_f32_e32 v104, v104
	v_exp_f32_e32 v105, v105
	v_mfma_f32_32x32x16_bf16 v[112:127], v[194:197], v[152:155], v[112:127]
	v_exp_f32_e32 v106, v106
	v_exp_f32_e32 v107, v107
	v_exp_f32_e32 v108, v108
	v_exp_f32_e32 v109, v109
	v_exp_f32_e32 v110, v110
	v_mfma_f32_32x32x16_bf16 v[112:127], v[198:201], v[156:159], v[112:127]
	v_exp_f32_e32 v111, v111
	v_add_f32_e32 v179, v96, v179
	v_add_f32_e32 v207, v97, v207
	v_add_f32_e32 v179, v98, v179
	v_add_f32_e32 v207, v99, v207
	s_waitcnt vmcnt(0)
	ds_read_b64_tr_b16 v[202:203], v232
	ds_read_b64_tr_b16 v[204:205], v232 offset:1024
	ds_read_b64_tr_b16 v[210:211], v232 offset:512
	ds_read_b64_tr_b16 v[212:213], v232 offset:1536
	ds_read_b64_tr_b16 v[220:221], v232 offset:2048
	ds_read_b64_tr_b16 v[222:223], v232 offset:3072
	v_add_f32_e32 v179, v100, v179
	v_add_f32_e32 v207, v101, v207
	v_add_f32_e32 v179, v102, v179
	v_add_f32_e32 v207, v103, v207
	v_add_f32_e32 v179, v104, v179
	v_add_f32_e32 v207, v105, v207
	s_waitcnt lgkmcnt(4)
	v_mfma_f32_32x32x16_bf16 v[48:63], v[202:205], v[64:67], v[48:63]
	v_add_f32_e32 v179, v106, v179
	v_add_f32_e32 v207, v107, v207
	v_add_f32_e32 v179, v108, v179
	v_add_f32_e32 v207, v109, v207
	v_add_f32_e32 v179, v110, v179
	v_add_f32_e32 v207, v111, v207
	v_cvt_pk_bf16_f32 v96, v96, v97
	v_cvt_pk_bf16_f32 v97, v98, v99
	v_cvt_pk_bf16_f32 v98, v100, v101
	v_cvt_pk_bf16_f32 v99, v102, v103
	v_cvt_pk_bf16_f32 v100, v104, v105
	v_cvt_pk_bf16_f32 v101, v106, v107
	v_cvt_pk_bf16_f32 v102, v108, v109
	v_cvt_pk_bf16_f32 v103, v110, v111
	v_mfma_f32_32x32x16_bf16 v[16:31], v[202:205], v[96:99], v[16:31]
	ds_read_b64_tr_b16 v[224:225], v232 offset:2560
	ds_read_b64_tr_b16 v[226:227], v232 offset:3584
	v_exp_f32_e32 v80, v80
	v_exp_f32_e32 v81, v81
	v_exp_f32_e32 v82, v82
	v_exp_f32_e32 v83, v83
	v_exp_f32_e32 v84, v84
	v_exp_f32_e32 v85, v85
	v_exp_f32_e32 v86, v86
	v_exp_f32_e32 v87, v87
	s_waitcnt lgkmcnt(4)
	v_mfma_f32_32x32x16_bf16 v[32:47], v[210:213], v[64:67], v[32:47]
	v_exp_f32_e32 v88, v88
	v_exp_f32_e32 v89, v89
	v_exp_f32_e32 v90, v90
	v_exp_f32_e32 v91, v91
	v_exp_f32_e32 v92, v92
	v_exp_f32_e32 v93, v93
	v_exp_f32_e32 v94, v94
	v_exp_f32_e32 v95, v95
	v_mfma_f32_32x32x16_bf16 v[0:15], v[210:213], v[96:99], v[0:15]
	ds_read_b64_tr_b16 v[202:203], v232 offset:4096
	ds_read_b64_tr_b16 v[204:205], v232 offset:5120
	v_add_f32_e32 v178, v80, v178
	v_add_f32_e32 v206, v81, v206
	v_add_f32_e32 v178, v82, v178
	v_add_f32_e32 v206, v83, v206
	v_add_f32_e32 v178, v84, v178
	v_add_f32_e32 v206, v85, v206
	v_add_f32_e32 v178, v86, v178
	v_add_f32_e32 v206, v87, v206
	s_waitcnt lgkmcnt(4)
	v_mfma_f32_32x32x16_bf16 v[48:63], v[220:223], v[68:71], v[48:63]
	v_add_f32_e32 v178, v88, v178
	v_add_f32_e32 v206, v89, v206
	v_add_f32_e32 v178, v90, v178
	v_add_f32_e32 v206, v91, v206
	v_add_f32_e32 v178, v92, v178
	v_add_f32_e32 v206, v93, v206
	v_add_f32_e32 v178, v94, v178
	v_add_f32_e32 v206, v95, v206
	v_mfma_f32_32x32x16_bf16 v[16:31], v[220:223], v[100:103], v[16:31]
	ds_read_b64_tr_b16 v[210:211], v232 offset:4608
	ds_read_b64_tr_b16 v[212:213], v232 offset:5632
	v_cvt_pk_bf16_f32 v80, v80, v81
	v_cvt_pk_bf16_f32 v81, v82, v83
	v_cvt_pk_bf16_f32 v82, v84, v85
	v_cvt_pk_bf16_f32 v83, v86, v87
	v_cvt_pk_bf16_f32 v84, v88, v89
	v_cvt_pk_bf16_f32 v85, v90, v91
	v_cvt_pk_bf16_f32 v86, v92, v93
	v_cvt_pk_bf16_f32 v87, v94, v95
	s_waitcnt lgkmcnt(4)
	v_mfma_f32_32x32x16_bf16 v[32:47], v[224:227], v[68:71], v[32:47]
	v_exp_f32_e32 v112, v112
	v_exp_f32_e32 v113, v113
	v_exp_f32_e32 v114, v114
	v_exp_f32_e32 v115, v115
	v_exp_f32_e32 v116, v116
	v_exp_f32_e32 v117, v117
	v_exp_f32_e32 v118, v118
	v_exp_f32_e32 v119, v119
	v_mfma_f32_32x32x16_bf16 v[0:15], v[224:227], v[100:103], v[0:15]
	ds_read_b64_tr_b16 v[220:221], v232 offset:6144
	ds_read_b64_tr_b16 v[222:223], v232 offset:7168
	v_exp_f32_e32 v120, v120
	v_exp_f32_e32 v121, v121
	v_exp_f32_e32 v122, v122
	v_exp_f32_e32 v123, v123
	v_exp_f32_e32 v124, v124
	v_exp_f32_e32 v125, v125
	v_exp_f32_e32 v126, v126
	v_exp_f32_e32 v127, v127
	s_waitcnt lgkmcnt(4)
	v_mfma_f32_32x32x16_bf16 v[48:63], v[202:205], v[80:83], v[48:63]
	v_add_f32_e32 v179, v112, v179
	v_add_f32_e32 v207, v113, v207
	v_add_f32_e32 v179, v114, v179
	v_add_f32_e32 v207, v115, v207
	v_add_f32_e32 v179, v116, v179
	v_add_f32_e32 v207, v117, v207
	v_add_f32_e32 v179, v118, v179
	v_add_f32_e32 v207, v119, v207
	v_add_f32_e32 v179, v120, v179
	v_add_f32_e32 v207, v121, v207
	v_add_f32_e32 v179, v122, v179
	v_add_f32_e32 v207, v123, v207
	v_add_f32_e32 v179, v124, v179
	v_add_f32_e32 v207, v125, v207
	v_add_f32_e32 v179, v126, v179
	v_add_f32_e32 v207, v127, v207
	v_cvt_pk_bf16_f32 v112, v112, v113
	v_cvt_pk_bf16_f32 v113, v114, v115
	v_cvt_pk_bf16_f32 v114, v116, v117
	v_cvt_pk_bf16_f32 v115, v118, v119
	v_cvt_pk_bf16_f32 v116, v120, v121
	v_cvt_pk_bf16_f32 v117, v122, v123
	v_cvt_pk_bf16_f32 v118, v124, v125
	v_cvt_pk_bf16_f32 v119, v126, v127
	v_mfma_f32_32x32x16_bf16 v[16:31], v[202:205], v[112:115], v[16:31]
	ds_read_b64_tr_b16 v[224:225], v232 offset:6656
	ds_read_b64_tr_b16 v[226:227], v232 offset:7680
	s_waitcnt lgkmcnt(4)
	v_mfma_f32_32x32x16_bf16 v[32:47], v[210:213], v[80:83], v[32:47]
	v_mfma_f32_32x32x16_bf16 v[0:15], v[210:213], v[112:115], v[0:15]
	s_waitcnt lgkmcnt(2)
	v_mfma_f32_32x32x16_bf16 v[48:63], v[220:223], v[84:87], v[48:63]
	v_mfma_f32_32x32x16_bf16 v[16:31], v[220:223], v[116:119], v[16:31]
	s_waitcnt lgkmcnt(0)
	v_mfma_f32_32x32x16_bf16 v[32:47], v[224:227], v[84:87], v[32:47]
	v_mfma_f32_32x32x16_bf16 v[0:15], v[224:227], v[116:119], v[0:15]
	s_nop 7
	v_add_f32_e32 v178, v178, v206
	v_add_f32_e32 v179, v179, v207
	s_nop 3
	s_branch .LBB0_488
.LBB0_502:
	s_and_b64 vcc, exec, s[0:1]
	s_cbranch_vccz .LBB0_489
	s_lshl_b32 s0, s16, 4
	s_and_b32 s0, s0, 0x70
	s_bfe_u32 s1, s16, 0x40003
	s_or_b32 s4, s0, s1
	s_ashr_i32 s5, s16, 7
	s_max_i32 s6, s4, 4
	s_min_i32 s6, s6, 0x7c
	s_add_i32 s6, s6, -4
	s_lshl_b32 s7, s5, 13
	s_lshl_b32 s8, s4, 6
	s_add_i32 s8, s8, s7
	s_lshl_b32 s9, s6, 6
	s_add_i32 s9, s9, s7
	s_lshl_b32 s17, s5, 8
	s_add_i32 s17, s17, 0x4000
	v_readlane_b32 s10, v251, 44
	v_readlane_b32 s14, v255, 16
	v_readlane_b32 s15, v255, 17
	v_readlane_b32 s18, v255, 12
	v_readlane_b32 s19, v255, 13
	v_mbcnt_lo_u32_b32 v237, -1, 0
	v_mbcnt_hi_u32_b32 v237, -1, v237
	s_lshr_b32 s10, s10, 6
	v_and_b32_e32 v238, 31, v237
	v_lshrrev_b32_e32 v239, 5, v237
	s_sub_i32 s11, s6, s4
	s_add_i32 s11, s11, 7
	s_mul_i32 s12, s10, 15
	s_add_i32 s11, s11, s12
	v_add_u32_e32 v240, s11, v239
	v_min_u32_e32 v241, 30, v238
	v_mad_u32_u24 v240, v240, 31, v241
	v_lshlrev_b32_e32 v240, 2, v240
	global_load_dword v242, v240, s[14:15]
	global_load_dword v243, v240, s[14:15] offset:248
	global_load_dword v244, v240, s[14:15] offset:496
	global_load_dword v245, v240, s[14:15] offset:744
	v_add_u32_e32 v180, s8, v238
	v_mov_b32_e32 v181, 0
	v_mov_b32_e32 v177, 0
	v_add_u32_e32 v176, 32, v180
	v_lshlrev_b32_e32 v174, 2, v239
	v_lshlrev_b32_e32 v246, 4, v239
	v_mov_b32_e32 v247, 0
	v_lshl_add_u64 v[246:247], v[246:247], 0, s[18:19]
	v_mad_i64_i32 v[248:249], s[0:1], v180, s71, v[246:247]
	v_mad_i64_i32 v[246:247], s[0:1], v176, s71, v[246:247]
	global_load_dwordx4 v[128:131], v[248:249], off
	global_load_dwordx4 v[132:135], v[248:249], off offset:32
	global_load_dwordx4 v[136:139], v[248:249], off offset:64
	global_load_dwordx4 v[140:143], v[248:249], off offset:96
	global_load_dwordx4 v[144:147], v[246:247], off
	global_load_dwordx4 v[148:151], v[246:247], off offset:32
	global_load_dwordx4 v[152:155], v[246:247], off offset:64
	global_load_dwordx4 v[156:159], v[246:247], off offset:96
	s_mul_i32 s12, s9, 0x1200
	s_add_u32 s20, s18, s12
	s_addc_u32 s21, s19, 0
	s_add_u32 s22, s20, 0x800
	s_addc_u32 s23, s21, 0
	s_add_u32 s20, s20, 0x400
	s_addc_u32 s21, s21, 0
	v_lshrrev_b32_e32 v214, 3, v237
	v_mul_u32_u24_e32 v214, 0x1200, v214
	v_lshrrev_b32_e32 v215, 4, v237
	v_xor_b32_e32 v215, v215, v237
	v_and_b32_e32 v215, 7, v215
	v_lshl_add_u32 v234, v215, 4, v214
	v_xor_b32_e32 v235, 64, v234
	v_lshrrev_b32_e32 v214, 2, v238
	v_mul_u32_u24_e32 v214, 0x1200, v214
	v_lshl_add_u32 v214, v239, 6, v214
	v_and_b32_e32 v215, 3, v237
	v_lshl_add_u32 v236, v215, 4, v214
	s_add_i32 m0, s87, 0x2000
	s_nop 0
	global_load_lds_dwordx4 v234, s[20:21]
	s_add_i32 m0, s87, 0x2400
	s_add_u32 s28, s20, 0x9000
	s_addc_u32 s29, s21, 0
	global_load_lds_dwordx4 v235, s[28:29]
	s_add_i32 m0, s87, 0x2800
	s_add_u32 s28, s20, 0x12000
	s_addc_u32 s29, s21, 0
	global_load_lds_dwordx4 v234, s[28:29]
	s_add_i32 m0, s87, 0x2c00
	s_add_u32 s28, s20, 0x1b000
	s_addc_u32 s29, s21, 0
	global_load_lds_dwordx4 v235, s[28:29]
	s_add_i32 m0, s87, 0x3000
	s_add_u32 s28, s20, 0x24000
	s_addc_u32 s29, s21, 0
	global_load_lds_dwordx4 v234, s[28:29]
	s_add_i32 m0, s87, 0x3400
	s_add_u32 s28, s20, 0x2d000
	s_addc_u32 s29, s21, 0
	global_load_lds_dwordx4 v235, s[28:29]
	s_add_i32 m0, s87, 0x3800
	s_add_u32 s28, s20, 0x36000
	s_addc_u32 s29, s21, 0
	global_load_lds_dwordx4 v234, s[28:29]
	s_add_i32 m0, s87, 0x3c00
	s_add_u32 s28, s20, 0x3f000
	s_addc_u32 s29, s21, 0
	global_load_lds_dwordx4 v235, s[28:29]
	s_mov_b32 m0, s87
	s_nop 0
	global_load_lds_dwordx4 v236, s[22:23]
	s_add_i32 m0, s87, 0x400
	s_add_u32 s28, s22, 0x9000
	s_addc_u32 s29, s23, 0
	global_load_lds_dwordx4 v236, s[28:29]
	s_add_i32 m0, s87, 0x800
	s_add_u32 s28, s22, 0x12000
	s_addc_u32 s29, s23, 0
	global_load_lds_dwordx4 v236, s[28:29]
	s_add_i32 m0, s87, 0xc00
	s_add_u32 s28, s22, 0x1b000
	s_addc_u32 s29, s23, 0
	global_load_lds_dwordx4 v236, s[28:29]
	s_add_i32 m0, s87, 0x1000
	s_add_u32 s28, s22, 0x24000
	s_addc_u32 s29, s23, 0
	global_load_lds_dwordx4 v236, s[28:29]
	s_add_i32 m0, s87, 0x1400
	s_add_u32 s28, s22, 0x2d000
	s_addc_u32 s29, s23, 0
	global_load_lds_dwordx4 v236, s[28:29]
	s_add_i32 m0, s87, 0x1800
	s_add_u32 s28, s22, 0x36000
	s_addc_u32 s29, s23, 0
	global_load_lds_dwordx4 v236, s[28:29]
	s_add_i32 m0, s87, 0x1c00
	s_add_u32 s28, s22, 0x3f000
	s_addc_u32 s29, s23, 0
	global_load_lds_dwordx4 v236, s[28:29]
	v_lshlrev_b32_e32 v214, 7, v238
	v_add_u32_e32 v214, s87, v214
	v_lshrrev_b32_e32 v215, 1, v237
	v_mov_b32_e32 v219, v239
	v_xor_b32_e32 v219, v219, v215
	v_and_b32_e32 v219, 7, v219
	v_lshl_add_u32 v228, v219, 4, v214
	v_add_u32_e32 v219, 2, v239
	v_xor_b32_e32 v219, v219, v215
	v_and_b32_e32 v219, 7, v219
	v_lshl_add_u32 v229, v219, 4, v214
	v_add_u32_e32 v219, 4, v239
	v_xor_b32_e32 v219, v219, v215
	v_and_b32_e32 v219, 7, v219
	v_lshl_add_u32 v230, v219, 4, v214
	v_add_u32_e32 v219, 6, v239
	v_xor_b32_e32 v219, v219, v215
	v_and_b32_e32 v219, 7, v219
	v_lshl_add_u32 v231, v219, 4, v214
	v_lshrrev_b32_e32 v214, 2, v237
	v_and_b32_e32 v214, 3, v214
	v_lshl_or_b32 v214, v239, 2, v214
	v_lshlrev_b32_e32 v214, 6, v214
	v_lshlrev_b32_e32 v215, 1, v237
	v_and_b32_e32 v215, 32, v215
	v_and_b32_e32 v219, 3, v237
	v_lshlrev_b32_e32 v219, 3, v219
	v_add3_u32 v232, v214, v215, v219
	v_add_u32_e32 v232, s87, v232
	v_lshlrev_b32_e32 v214, 4, v239
	v_lshlrev_b32_e32 v215, 2, v238
	v_sub_u32_e32 v214, v214, v215
	s_add_i32 s12, s87, 0x3fbc
	v_add_u32_e32 v233, s12, v214
	v_mov_b32_e32 v0, 0
	v_mov_b32_e32 v1, 0
	v_mov_b32_e32 v2, 0
	v_mov_b32_e32 v3, 0
	v_mov_b32_e32 v4, 0
	v_mov_b32_e32 v5, 0
	v_mov_b32_e32 v6, 0
	v_mov_b32_e32 v7, 0
	v_mov_b32_e32 v8, 0
	v_mov_b32_e32 v9, 0
	v_mov_b32_e32 v10, 0
	v_mov_b32_e32 v11, 0
	v_mov_b32_e32 v12, 0
	v_mov_b32_e32 v13, 0
	v_mov_b32_e32 v14, 0
	v_mov_b32_e32 v15, 0
	v_mov_b32_e32 v16, 0
	v_mov_b32_e32 v17, 0
	v_mov_b32_e32 v18, 0
	v_mov_b32_e32 v19, 0
	v_mov_b32_e32 v20, 0
	v_mov_b32_e32 v21, 0
	v_mov_b32_e32 v22, 0
	v_mov_b32_e32 v23, 0
	v_mov_b32_e32 v24, 0
	v_mov_b32_e32 v25, 0
	v_mov_b32_e32 v26, 0
	v_mov_b32_e32 v27, 0
	v_mov_b32_e32 v28, 0
	v_mov_b32_e32 v29, 0
	v_mov_b32_e32 v30, 0
	v_mov_b32_e32 v31, 0
	v_mov_b32_e32 v32, 0
	v_mov_b32_e32 v33, 0
	v_mov_b32_e32 v34, 0
	v_mov_b32_e32 v35, 0
	v_mov_b32_e32 v36, 0
	v_mov_b32_e32 v37, 0
	v_mov_b32_e32 v38, 0
	v_mov_b32_e32 v39, 0
	v_mov_b32_e32 v40, 0
	v_mov_b32_e32 v41, 0
	v_mov_b32_e32 v42, 0
	v_mov_b32_e32 v43, 0
	v_mov_b32_e32 v44, 0
	v_mov_b32_e32 v45, 0
	v_mov_b32_e32 v46, 0
	v_mov_b32_e32 v47, 0
	v_mov_b32_e32 v48, 0
	v_mov_b32_e32 v49, 0
	v_mov_b32_e32 v50, 0
	v_mov_b32_e32 v51, 0
	v_mov_b32_e32 v52, 0
	v_mov_b32_e32 v53, 0
	v_mov_b32_e32 v54, 0
	v_mov_b32_e32 v55, 0
	v_mov_b32_e32 v56, 0
	v_mov_b32_e32 v57, 0
	v_mov_b32_e32 v58, 0
	v_mov_b32_e32 v59, 0
	v_mov_b32_e32 v60, 0
	v_mov_b32_e32 v61, 0
	v_mov_b32_e32 v62, 0
	v_mov_b32_e32 v63, 0
	v_mov_b32_e32 v178, 0
	v_mov_b32_e32 v179, 0
	v_mov_b32_e32 v206, 0
	v_mov_b32_e32 v207, 0
	s_waitcnt vmcnt(24)
	v_cmp_ne_u32_e32 vcc, 31, v238
	v_lshl_add_u32 v214, v237, 2, s87
	v_mul_f32_e32 v242, 0x3fb8aa3b, v242
	v_mul_f32_e32 v243, 0x3fb8aa3b, v243
	v_mul_f32_e32 v244, 0x3fb8aa3b, v244
	v_mul_f32_e32 v245, 0x3fb8aa3b, v245
	s_nop 0
	v_cndmask_b32_e32 v242, 0, v242, vcc
	v_cndmask_b32_e32 v243, 0, v243, vcc
	v_cndmask_b32_e32 v244, 0, v244, vcc
	v_cndmask_b32_e32 v245, 0, v245, vcc
	ds_write_b32 v214, v242 offset:16384
	ds_write_b32 v214, v243 offset:16640
	ds_write_b32 v214, v244 offset:16896
	ds_write_b32 v214, v245 offset:17152
	s_mov_b32 s24, 0
